# P8 only: accumulator zeroing folded into a peeled first K-iteration (first MFMA per tile takes C=0); 64 VALU zeroing ops per unit and wave removed
# baseline (speedup 1.0000x reference)
; template <class Epi, class Sched, bool ALIGN_EPI = false, bool SP2 = false, bool F8 = false>
; __device__ __forceinline__ void gemm_phase(PG8_LAS unsigned char* lds, const Gemm g, const Sched& S, const Epi& E) {
;     ...
;         const char* nA = has_next ? PG8_ABASE(nxt.pm) : cA; const char* nB = has_next ? (const char*)g.Bt + (size_t)nxt.pn * tstep : cB;
;     ...
; #pragma unroll
;         for (int a = 0; a < 2; ++a)
; #pragma unroll
;             for (int b = 0; b < 2; ++b)
; #pragma unroll
;                 for (int m = 0; m < 4; ++m)
; #pragma unroll
;                     for (int n = 0; n < 2; ++n) acc[a][b][m][n] = (f32x4){0.f, 0.f, 0.f, 0.f};
;         cur = nxt; cA = nA; cB = nB; ++ui;
.LBB0_916:
	s_ashr_i32 s51, s50, 31
	s_lshl_b64 s[24:25], s[50:51], 20
	s_add_u32 s54, s42, s24
	s_addc_u32 s55, s43, s25
	s_and_b64 s[6:7], s[6:7], exec
	s_cselect_b32 s15, s55, s59
	s_cselect_b32 s26, s54, s58
	s_add_u32 s27, s58, 0x100
	s_addc_u32 s28, s59, 0
	s_mov_b32 s29, -2
	s_cmp_lg_u64 s[12:13], 0
	s_cbranch_scc1 .Lk3_Yz
	s_branch .Lk3_Xz

; #define PG8_STAGE(bufoff, gbase, voff) do { _Pragma("unroll") for (int _i = 0; _i < 2; ++_i) \
;         __builtin_amdgcn_global_load_lds((const unsigned*)((const char*)(gbase) + (voff)[_i]), (PG8_LAS unsigned*)(lds + (bufoff) + ldsw + _i * 8192), 16, 0, 0); } while (0)
; #define PG8_LDA(dst, b, h) do { _Pragma("unroll") for (int m = 0; m < 4; ++m) _Pragma("unroll") for (int k = 0; k < 2; ++k) dst[m][k] = *(const PG8_LAS bf16x8*)(lds + PG8_SA(b, h) + aoff + m * 2048 + k * 1024); } while (0)
; #define PG8_LDB(dst, b, h) do { _Pragma("unroll") for (int n = 0; n < 2; ++n) _Pragma("unroll") for (int k = 0; k < 2; ++k) dst[n][k] = *(const PG8_LAS bf16x8*)(lds + PG8_SB(b, h) + boff + n * 2048 + k * 1024); } while (0)
; #define PG8_WAIT_V(n) asm volatile("s_waitcnt vmcnt(" #n ")" ::: "memory")
; #define PG8_WAIT_L(n) asm volatile("s_waitcnt lgkmcnt(" #n ")" ::: "memory")
; #define PG8_BAR __builtin_amdgcn_s_barrier()
; #define PG8_SCHED __builtin_amdgcn_sched_barrier(0)
; template <class Epi, class Sched, bool ALIGN_EPI = false, bool SP2 = false, bool F8 = false>
; __device__ __forceinline__ void gemm_phase(PG8_LAS unsigned char* lds, const Gemm g, const Sched& S, const Epi& E) {
;     ...
;             const bool last = (t == nt - 2);
;             const char* a1 = cA + (size_t)(t + 1) * kstep;
;             const char* a2 = last ? nA : cA + (size_t)(t + 2) * kstep; const char* b2 = last ? nB : cB + (size_t)(t + 2) * kstep;
;             const char* a3 = a2 + kstep; const char* b3 = b2 + kstep;
;             if (last && has_next) S.a_ready(nxt);
;             if constexpr (SP2) {
;             PG8_LDB(B0, 0, 0); PG8_LDB(B1, 0, 1); PG8_SCHED; PG8_LDA(At, 0, 0); PG8_STAGE(PG8_SA(1, 1), a1 + hstepA, voffA);
;             PG8_WAIT_V(8); PG8_WAIT_L(0); PG8_BAR; PG8_MMA(0, 0, At, B0); PG8_MMA(0, 1, At, B1); PG8_BAR; PG8_SCHED;
.Lk3_Y:
	ds_read_b128 v[146:149], v175
	ds_read_b128 v[150:153], v175 offset:1024
	ds_read_b128 v[154:157], v175 offset:2048
	ds_read_b128 v[158:161], v175 offset:3072
	ds_read_b128 v[162:165], v176
	ds_read_b128 v[166:169], v176 offset:1024
	ds_read_b128 v[186:189], v176 offset:2048
	ds_read_b128 v[190:193], v176 offset:3072
	s_add_u32 s6, s56, 0x100
	s_addc_u32 s7, s57, 0
	s_cmp_eq_u32 s29, 28
	s_cselect_b32 s61, s53, s7
	s_cselect_b32 s60, s52, s6
	s_cselect_b32 s59, s15, s28
	s_cselect_b32 s58, s26, s27
	ds_read_b128 v[194:197], v177
	ds_read_b128 v[198:201], v177 offset:1024
	ds_read_b128 v[202:205], v177 offset:2048
	ds_read_b128 v[206:209], v177 offset:3072
	ds_read_b128 v[210:213], v177 offset:4096
	ds_read_b128 v[218:221], v177 offset:5120
	ds_read_b128 v[222:225], v177 offset:6144
	ds_read_b128 v[226:229], v177 offset:7168
	s_add_i32 m0, s65, 0xc000
	s_nop 0
	global_load_lds_dwordx4 v138, s[56:57]
	s_add_i32 m0, s65, 0xe000
	s_nop 0
	global_load_lds_dwordx4 v140, s[56:57]
	s_waitcnt vmcnt(8)
	s_waitcnt lgkmcnt(0)
	s_barrier
	s_setprio 3
	s_waitcnt lgkmcnt(0)
	v_mfma_f32_16x16x32_bf16 v[126:129], v[146:149], v[194:197], v[126:129]
	v_mfma_f32_16x16x32_bf16 v[122:125], v[154:157], v[194:197], v[122:125]
	v_mfma_f32_16x16x32_bf16 v[118:121], v[146:149], v[202:205], v[118:121]
	v_mfma_f32_16x16x32_bf16 v[114:117], v[154:157], v[202:205], v[114:117]
	v_mfma_f32_16x16x32_bf16 v[110:113], v[146:149], v[210:213], v[110:113]
	v_mfma_f32_16x16x32_bf16 v[102:105], v[154:157], v[210:213], v[102:105]
	v_mfma_f32_16x16x32_bf16 v[94:97], v[146:149], v[222:225], v[94:97]
	v_mfma_f32_16x16x32_bf16 v[86:89], v[154:157], v[222:225], v[86:89]
	v_mfma_f32_16x16x32_bf16 v[126:129], v[150:153], v[198:201], v[126:129]
	v_mfma_f32_16x16x32_bf16 v[122:125], v[158:161], v[198:201], v[122:125]
	v_mfma_f32_16x16x32_bf16 v[118:121], v[150:153], v[206:209], v[118:121]
	v_mfma_f32_16x16x32_bf16 v[114:117], v[158:161], v[206:209], v[114:117]
	v_mfma_f32_16x16x32_bf16 v[110:113], v[150:153], v[218:221], v[110:113]
	v_mfma_f32_16x16x32_bf16 v[102:105], v[158:161], v[218:221], v[102:105]
	v_mfma_f32_16x16x32_bf16 v[94:97], v[150:153], v[226:229], v[94:97]
	v_mfma_f32_16x16x32_bf16 v[86:89], v[158:161], v[226:229], v[86:89]


; #define PG8_STAGE(bufoff, gbase, voff) do { _Pragma("unroll") for (int _i = 0; _i < 2; ++_i) \
;         __builtin_amdgcn_global_load_lds((const unsigned*)((const char*)(gbase) + (voff)[_i]), (PG8_LAS unsigned*)(lds + (bufoff) + ldsw + _i * 8192), 16, 0, 0); } while (0)
; #define PG8_LDA(dst, b, h) do { _Pragma("unroll") for (int m = 0; m < 4; ++m) _Pragma("unroll") for (int k = 0; k < 2; ++k) dst[m][k] = *(const PG8_LAS bf16x8*)(lds + PG8_SA(b, h) + aoff + m * 2048 + k * 1024); } while (0)
; #define PG8_WAIT_V(n) asm volatile("s_waitcnt vmcnt(" #n ")" ::: "memory")
; #define PG8_WAIT_L(n) asm volatile("s_waitcnt lgkmcnt(" #n ")" ::: "memory")
; #define PG8_BAR __builtin_amdgcn_s_barrier()
; #define PG8_SCHED __builtin_amdgcn_sched_barrier(0)
; template <class Epi, class Sched, bool ALIGN_EPI = false, bool SP2 = false, bool F8 = false>
; __device__ __forceinline__ void gemm_phase(PG8_LAS unsigned char* lds, const Gemm g, const Sched& S, const Epi& E) {
;     ...
;             PG8_WAIT_V(8); PG8_WAIT_L(0); PG8_BAR; PG8_MMA(0, 0, At, B0); PG8_MMA(0, 1, At, B1); PG8_BAR; PG8_SCHED;
;             PG8_LDA(At, 0, 1); PG8_STAGE(PG8_SB(0, 0), b2, voffB); PG8_STAGE(PG8_SB(0, 1), b2 + hstep, voffB); PG8_STAGE(PG8_SA(0, 0), a2, voffA);
;             PG8_WAIT_V(8); PG8_WAIT_L(0); PG8_BAR; PG8_MMA(1, 0, At, B0); PG8_MMA(1, 1, At, B1); PG8_BAR; PG8_SCHED;
	v_mfma_f32_16x16x32_bf16 v[106:109], v[162:165], v[194:197], v[106:109]
	v_mfma_f32_16x16x32_bf16 v[98:101], v[186:189], v[194:197], v[98:101]
	v_mfma_f32_16x16x32_bf16 v[90:93], v[162:165], v[202:205], v[90:93]
	v_mfma_f32_16x16x32_bf16 v[82:85], v[186:189], v[202:205], v[82:85]
	v_mfma_f32_16x16x32_bf16 v[78:81], v[162:165], v[210:213], v[78:81]
	v_mfma_f32_16x16x32_bf16 v[74:77], v[186:189], v[210:213], v[74:77]
	v_mfma_f32_16x16x32_bf16 v[70:73], v[162:165], v[222:225], v[70:73]
	v_mfma_f32_16x16x32_bf16 v[66:69], v[186:189], v[222:225], v[66:69]
	v_mfma_f32_16x16x32_bf16 v[106:109], v[166:169], v[198:201], v[106:109]
	v_mfma_f32_16x16x32_bf16 v[98:101], v[190:193], v[198:201], v[98:101]
	v_mfma_f32_16x16x32_bf16 v[90:93], v[166:169], v[206:209], v[90:93]
	v_mfma_f32_16x16x32_bf16 v[82:85], v[190:193], v[206:209], v[82:85]
	v_mfma_f32_16x16x32_bf16 v[78:81], v[166:169], v[218:221], v[78:81]
	v_mfma_f32_16x16x32_bf16 v[74:77], v[190:193], v[218:221], v[74:77]
	v_mfma_f32_16x16x32_bf16 v[70:73], v[166:169], v[226:229], v[70:73]
	v_mfma_f32_16x16x32_bf16 v[66:69], v[190:193], v[226:229], v[66:69]
	s_setprio 0
	ds_read_b128 v[194:197], v177 offset:16384
	ds_read_b128 v[198:201], v177 offset:17408
	ds_read_b128 v[202:205], v177 offset:18432
	ds_read_b128 v[206:209], v177 offset:19456
	ds_read_b128 v[210:213], v177 offset:20480
	ds_read_b128 v[218:221], v177 offset:21504
	ds_read_b128 v[222:225], v177 offset:22528
	ds_read_b128 v[226:229], v177 offset:23552
	s_add_u32 s98, s58, 0x80000
	s_addc_u32 s99, s59, 0
	s_add_i32 s100, s75, s62
	s_add_i32 s101, s76, s62
	s_mov_b32 m0, s100
	s_nop 0
	global_load_lds_dwordx4 v134, s[58:59]
	s_add_i32 m0, s100, 0x2000
	s_nop 0
	global_load_lds_dwordx4 v130, s[58:59]
	s_mov_b32 m0, s101
	s_nop 0
	global_load_lds_dwordx4 v134, s[98:99]
	s_add_i32 m0, s101, 0x2000
	s_nop 0
	global_load_lds_dwordx4 v130, s[98:99]
	s_mov_b32 m0, s65
	s_nop 0
	global_load_lds_dwordx4 v136, s[60:61]
	s_mov_b32 m0, s66
	s_nop 0
	global_load_lds_dwordx4 v132, s[60:61]
	s_waitcnt vmcnt(8)
	s_waitcnt lgkmcnt(0)
	s_barrier
	s_setprio 3
	s_waitcnt lgkmcnt(0)
	v_mfma_f32_16x16x32_bf16 v[62:65], v[146:149], v[194:197], v[62:65]
	v_mfma_f32_16x16x32_bf16 v[58:61], v[154:157], v[194:197], v[58:61]
	v_mfma_f32_16x16x32_bf16 v[54:57], v[146:149], v[202:205], v[54:57]
	v_mfma_f32_16x16x32_bf16 v[50:53], v[154:157], v[202:205], v[50:53]
	v_mfma_f32_16x16x32_bf16 v[38:41], v[146:149], v[210:213], v[38:41]
	v_mfma_f32_16x16x32_bf16 v[34:37], v[154:157], v[210:213], v[34:37]
	v_mfma_f32_16x16x32_bf16 v[22:25], v[146:149], v[222:225], v[22:25]
	v_mfma_f32_16x16x32_bf16 v[18:21], v[154:157], v[222:225], v[18:21]
	v_mfma_f32_16x16x32_bf16 v[62:65], v[150:153], v[198:201], v[62:65]
	v_mfma_f32_16x16x32_bf16 v[58:61], v[158:161], v[198:201], v[58:61]
	v_mfma_f32_16x16x32_bf16 v[54:57], v[150:153], v[206:209], v[54:57]
	v_mfma_f32_16x16x32_bf16 v[50:53], v[158:161], v[206:209], v[50:53]
	v_mfma_f32_16x16x32_bf16 v[38:41], v[150:153], v[218:221], v[38:41]
	v_mfma_f32_16x16x32_bf16 v[34:37], v[158:161], v[218:221], v[34:37]
	v_mfma_f32_16x16x32_bf16 v[22:25], v[150:153], v[226:229], v[22:25]
	v_mfma_f32_16x16x32_bf16 v[18:21], v[158:161], v[226:229], v[18:21]


; #define PG8_STAGE(bufoff, gbase, voff) do { _Pragma("unroll") for (int _i = 0; _i < 2; ++_i) \
;         __builtin_amdgcn_global_load_lds((const unsigned*)((const char*)(gbase) + (voff)[_i]), (PG8_LAS unsigned*)(lds + (bufoff) + ldsw + _i * 8192), 16, 0, 0); } while (0)
; #define PG8_LDA(dst, b, h) do { _Pragma("unroll") for (int m = 0; m < 4; ++m) _Pragma("unroll") for (int k = 0; k < 2; ++k) dst[m][k] = *(const PG8_LAS bf16x8*)(lds + PG8_SA(b, h) + aoff + m * 2048 + k * 1024); } while (0)
; #define PG8_LDB(dst, b, h) do { _Pragma("unroll") for (int n = 0; n < 2; ++n) _Pragma("unroll") for (int k = 0; k < 2; ++k) dst[n][k] = *(const PG8_LAS bf16x8*)(lds + PG8_SB(b, h) + boff + n * 2048 + k * 1024); } while (0)
; #define PG8_WAIT_V(n) asm volatile("s_waitcnt vmcnt(" #n ")" ::: "memory")
; #define PG8_WAIT_L(n) asm volatile("s_waitcnt lgkmcnt(" #n ")" ::: "memory")
; #define PG8_BAR __builtin_amdgcn_s_barrier()
; #define PG8_SCHED __builtin_amdgcn_sched_barrier(0)
; template <class Epi, class Sched, bool ALIGN_EPI = false, bool SP2 = false, bool F8 = false>
; __device__ __forceinline__ void gemm_phase(PG8_LAS unsigned char* lds, const Gemm g, const Sched& S, const Epi& E) {
;     ...
;             PG8_WAIT_V(8); PG8_WAIT_L(0); PG8_BAR; PG8_MMA(1, 0, At, B0); PG8_MMA(1, 1, At, B1); PG8_BAR; PG8_SCHED;
;             PG8_LDB(B0, 1, 0); PG8_LDB(B1, 1, 1); PG8_SCHED; PG8_LDA(At, 1, 0); PG8_STAGE(PG8_SA(0, 1), a2 + hstepA, voffA);
;             PG8_WAIT_V(8); PG8_WAIT_L(0); PG8_BAR; PG8_MMA(0, 0, At, B0); PG8_MMA(0, 1, At, B1); PG8_BAR; PG8_SCHED;
	v_mfma_f32_16x16x32_bf16 v[46:49], v[162:165], v[194:197], v[46:49]
	v_mfma_f32_16x16x32_bf16 v[42:45], v[186:189], v[194:197], v[42:45]
	v_mfma_f32_16x16x32_bf16 v[30:33], v[162:165], v[202:205], v[30:33]
	v_mfma_f32_16x16x32_bf16 v[26:29], v[186:189], v[202:205], v[26:29]
	v_mfma_f32_16x16x32_bf16 v[14:17], v[162:165], v[210:213], v[14:17]
	v_mfma_f32_16x16x32_bf16 v[10:13], v[186:189], v[210:213], v[10:13]
	v_mfma_f32_16x16x32_bf16 v[6:9], v[162:165], v[222:225], v[6:9]
	v_mfma_f32_16x16x32_bf16 v[2:5], v[186:189], v[222:225], v[2:5]
	v_mfma_f32_16x16x32_bf16 v[46:49], v[166:169], v[198:201], v[46:49]
	v_mfma_f32_16x16x32_bf16 v[42:45], v[190:193], v[198:201], v[42:45]
	v_mfma_f32_16x16x32_bf16 v[30:33], v[166:169], v[206:209], v[30:33]
	v_mfma_f32_16x16x32_bf16 v[26:29], v[190:193], v[206:209], v[26:29]
	v_mfma_f32_16x16x32_bf16 v[14:17], v[166:169], v[218:221], v[14:17]
	v_mfma_f32_16x16x32_bf16 v[10:13], v[190:193], v[218:221], v[10:13]
	v_mfma_f32_16x16x32_bf16 v[6:9], v[166:169], v[226:229], v[6:9]
	v_mfma_f32_16x16x32_bf16 v[2:5], v[190:193], v[226:229], v[2:5]
	s_setprio 0
	s_add_i32 s33, 0, 0x18000
	s_add_i32 s36, 0, 0x1c000
	v_add_u32_e32 v158, s33, v174
	v_add_u32_e32 v185, s36, v174
	ds_read_b128 v[146:149], v158
	ds_read_b128 v[150:153], v158 offset:1024
	ds_read_b128 v[154:157], v158 offset:2048
	ds_read_b128 v[158:161], v158 offset:3072
	ds_read_b128 v[162:165], v185
	ds_read_b128 v[166:169], v185 offset:1024
	ds_read_b128 v[186:189], v185 offset:2048
	ds_read_b128 v[190:193], v185 offset:3072
	ds_read_b128 v[194:197], v177 offset:32768
	ds_read_b128 v[198:201], v177 offset:33792
	ds_read_b128 v[202:205], v177 offset:34816
	ds_read_b128 v[206:209], v177 offset:35840
	ds_read_b128 v[210:213], v177 offset:36864
	ds_read_b128 v[218:221], v177 offset:37888
	ds_read_b128 v[222:225], v177 offset:38912
	ds_read_b128 v[226:229], v177 offset:39936
	s_add_u32 s98, s60, 0x100000
	s_addc_u32 s99, s61, 0
	s_mov_b32 m0, s67
	s_nop 0
	global_load_lds_dwordx4 v136, s[98:99]
	s_mov_b32 m0, s68
	s_nop 0
	global_load_lds_dwordx4 v132, s[98:99]
	s_waitcnt vmcnt(8)
	s_waitcnt lgkmcnt(0)
	s_barrier
	s_setprio 3
	s_waitcnt lgkmcnt(0)
	v_mfma_f32_16x16x32_bf16 v[126:129], v[146:149], v[194:197], v[126:129]
	v_mfma_f32_16x16x32_bf16 v[122:125], v[154:157], v[194:197], v[122:125]
	v_mfma_f32_16x16x32_bf16 v[118:121], v[146:149], v[202:205], v[118:121]
	v_mfma_f32_16x16x32_bf16 v[114:117], v[154:157], v[202:205], v[114:117]
	v_mfma_f32_16x16x32_bf16 v[110:113], v[146:149], v[210:213], v[110:113]
	v_mfma_f32_16x16x32_bf16 v[102:105], v[154:157], v[210:213], v[102:105]
	v_mfma_f32_16x16x32_bf16 v[94:97], v[146:149], v[222:225], v[94:97]
	v_mfma_f32_16x16x32_bf16 v[86:89], v[154:157], v[222:225], v[86:89]
	v_mfma_f32_16x16x32_bf16 v[126:129], v[150:153], v[198:201], v[126:129]
	v_mfma_f32_16x16x32_bf16 v[122:125], v[158:161], v[198:201], v[122:125]
	v_mfma_f32_16x16x32_bf16 v[118:121], v[150:153], v[206:209], v[118:121]
	v_mfma_f32_16x16x32_bf16 v[114:117], v[158:161], v[206:209], v[114:117]
	v_mfma_f32_16x16x32_bf16 v[110:113], v[150:153], v[218:221], v[110:113]
	v_mfma_f32_16x16x32_bf16 v[102:105], v[158:161], v[218:221], v[102:105]
	v_mfma_f32_16x16x32_bf16 v[94:97], v[150:153], v[226:229], v[94:97]
	v_mfma_f32_16x16x32_bf16 v[86:89], v[158:161], v[226:229], v[86:89]


; #define PG8_STAGE(bufoff, gbase, voff) do { _Pragma("unroll") for (int _i = 0; _i < 2; ++_i) \
;         __builtin_amdgcn_global_load_lds((const unsigned*)((const char*)(gbase) + (voff)[_i]), (PG8_LAS unsigned*)(lds + (bufoff) + ldsw + _i * 8192), 16, 0, 0); } while (0)
; #define PG8_LDA(dst, b, h) do { _Pragma("unroll") for (int m = 0; m < 4; ++m) _Pragma("unroll") for (int k = 0; k < 2; ++k) dst[m][k] = *(const PG8_LAS bf16x8*)(lds + PG8_SA(b, h) + aoff + m * 2048 + k * 1024); } while (0)
; #define PG8_WAIT_V(n) asm volatile("s_waitcnt vmcnt(" #n ")" ::: "memory")
; #define PG8_WAIT_L(n) asm volatile("s_waitcnt lgkmcnt(" #n ")" ::: "memory")
; #define PG8_BAR __builtin_amdgcn_s_barrier()
; #define PG8_SCHED __builtin_amdgcn_sched_barrier(0)
; template <class Epi, class Sched, bool ALIGN_EPI = false, bool SP2 = false, bool F8 = false>
; __device__ __forceinline__ void gemm_phase(PG8_LAS unsigned char* lds, const Gemm g, const Sched& S, const Epi& E) {
;     ...
;             PG8_WAIT_V(8); PG8_WAIT_L(0); PG8_BAR; PG8_MMA(0, 0, At, B0); PG8_MMA(0, 1, At, B1); PG8_BAR; PG8_SCHED;
;             PG8_LDA(At, 1, 1); PG8_STAGE(PG8_SB(1, 0), b3, voffB); PG8_STAGE(PG8_SB(1, 1), b3 + hstep, voffB); PG8_STAGE(PG8_SA(1, 0), a3, voffA);
;             PG8_WAIT_V(8); PG8_WAIT_L(0); PG8_BAR; PG8_MMA(1, 0, At, B0); PG8_MMA(1, 1, At, B1); PG8_BAR; PG8_SCHED;
	v_mfma_f32_16x16x32_bf16 v[106:109], v[162:165], v[194:197], v[106:109]
	v_mfma_f32_16x16x32_bf16 v[98:101], v[186:189], v[194:197], v[98:101]
	v_mfma_f32_16x16x32_bf16 v[90:93], v[162:165], v[202:205], v[90:93]
	v_mfma_f32_16x16x32_bf16 v[82:85], v[186:189], v[202:205], v[82:85]
	v_mfma_f32_16x16x32_bf16 v[78:81], v[162:165], v[210:213], v[78:81]
	v_mfma_f32_16x16x32_bf16 v[74:77], v[186:189], v[210:213], v[74:77]
	v_mfma_f32_16x16x32_bf16 v[70:73], v[162:165], v[222:225], v[70:73]
	v_mfma_f32_16x16x32_bf16 v[66:69], v[186:189], v[222:225], v[66:69]
	v_mfma_f32_16x16x32_bf16 v[106:109], v[166:169], v[198:201], v[106:109]
	v_mfma_f32_16x16x32_bf16 v[98:101], v[190:193], v[198:201], v[98:101]
	v_mfma_f32_16x16x32_bf16 v[90:93], v[166:169], v[206:209], v[90:93]
	v_mfma_f32_16x16x32_bf16 v[82:85], v[190:193], v[206:209], v[82:85]
	v_mfma_f32_16x16x32_bf16 v[78:81], v[166:169], v[218:221], v[78:81]
	v_mfma_f32_16x16x32_bf16 v[74:77], v[190:193], v[218:221], v[74:77]
	v_mfma_f32_16x16x32_bf16 v[70:73], v[166:169], v[226:229], v[70:73]
	v_mfma_f32_16x16x32_bf16 v[66:69], v[190:193], v[226:229], v[66:69]
	s_setprio 0
	ds_read_b128 v[194:197], v177 offset:49152
	ds_read_b128 v[198:201], v177 offset:50176
	ds_read_b128 v[202:205], v177 offset:51200
	ds_read_b128 v[206:209], v177 offset:52224
	ds_read_b128 v[210:213], v177 offset:53248
	ds_read_b128 v[218:221], v177 offset:54272
	ds_read_b128 v[222:225], v177 offset:55296
	ds_read_b128 v[226:229], v177 offset:56320
	s_add_u32 s98, s58, 0x80
	s_addc_u32 s99, s59, 0
	s_add_u32 s100, s58, 0x80080
	s_addc_u32 s101, s59, 0
	s_add_u32 s24, s60, 0x80
	s_addc_u32 s25, s61, 0
	s_add_i32 m0, s62, 0x18000
	s_nop 0
	global_load_lds_dwordx4 v134, s[98:99]
	s_add_i32 m0, s62, 0x1a000
	s_nop 0
	global_load_lds_dwordx4 v130, s[98:99]
	s_add_i32 m0, s62, 0x1c000
	s_nop 0
	global_load_lds_dwordx4 v134, s[100:101]
	s_add_i32 m0, s62, 0x1e000
	s_nop 0
	global_load_lds_dwordx4 v130, s[100:101]
	s_mov_b32 m0, s71
	s_nop 0
	global_load_lds_dwordx4 v136, s[24:25]
	s_mov_b32 m0, s72
	s_nop 0
	global_load_lds_dwordx4 v132, s[24:25]
	s_waitcnt vmcnt(8)
	s_waitcnt lgkmcnt(0)
	s_barrier
	s_setprio 3
	s_waitcnt lgkmcnt(0)
	v_mfma_f32_16x16x32_bf16 v[62:65], v[146:149], v[194:197], v[62:65]
	v_mfma_f32_16x16x32_bf16 v[58:61], v[154:157], v[194:197], v[58:61]
	v_mfma_f32_16x16x32_bf16 v[54:57], v[146:149], v[202:205], v[54:57]
	v_mfma_f32_16x16x32_bf16 v[50:53], v[154:157], v[202:205], v[50:53]
	v_mfma_f32_16x16x32_bf16 v[38:41], v[146:149], v[210:213], v[38:41]
	v_mfma_f32_16x16x32_bf16 v[34:37], v[154:157], v[210:213], v[34:37]
	v_mfma_f32_16x16x32_bf16 v[22:25], v[146:149], v[222:225], v[22:25]
	v_mfma_f32_16x16x32_bf16 v[18:21], v[154:157], v[222:225], v[18:21]
	v_mfma_f32_16x16x32_bf16 v[62:65], v[150:153], v[198:201], v[62:65]
	v_mfma_f32_16x16x32_bf16 v[58:61], v[158:161], v[198:201], v[58:61]
	v_mfma_f32_16x16x32_bf16 v[54:57], v[150:153], v[206:209], v[54:57]
	v_mfma_f32_16x16x32_bf16 v[50:53], v[158:161], v[206:209], v[50:53]
	v_mfma_f32_16x16x32_bf16 v[38:41], v[150:153], v[218:221], v[38:41]
	v_mfma_f32_16x16x32_bf16 v[34:37], v[158:161], v[218:221], v[34:37]
	v_mfma_f32_16x16x32_bf16 v[22:25], v[150:153], v[226:229], v[22:25]
	v_mfma_f32_16x16x32_bf16 v[18:21], v[158:161], v[226:229], v[18:21]


; #define PG8_STAGE(bufoff, gbase, voff) do { _Pragma("unroll") for (int _i = 0; _i < 2; ++_i) \
;         __builtin_amdgcn_global_load_lds((const unsigned*)((const char*)(gbase) + (voff)[_i]), (PG8_LAS unsigned*)(lds + (bufoff) + ldsw + _i * 8192), 16, 0, 0); } while (0)
; #define PG8_LDA(dst, b, h) do { _Pragma("unroll") for (int m = 0; m < 4; ++m) _Pragma("unroll") for (int k = 0; k < 2; ++k) dst[m][k] = *(const PG8_LAS bf16x8*)(lds + PG8_SA(b, h) + aoff + m * 2048 + k * 1024); } while (0)
; #define PG8_LDB(dst, b, h) do { _Pragma("unroll") for (int n = 0; n < 2; ++n) _Pragma("unroll") for (int k = 0; k < 2; ++k) dst[n][k] = *(const PG8_LAS bf16x8*)(lds + PG8_SB(b, h) + boff + n * 2048 + k * 1024); } while (0)
; #define PG8_WAIT_V(n) asm volatile("s_waitcnt vmcnt(" #n ")" ::: "memory")
; #define PG8_WAIT_L(n) asm volatile("s_waitcnt lgkmcnt(" #n ")" ::: "memory")
; #define PG8_BAR __builtin_amdgcn_s_barrier()
; #define PG8_SCHED __builtin_amdgcn_sched_barrier(0)
; template <class Epi, class Sched, bool ALIGN_EPI = false, bool SP2 = false, bool F8 = false>
; __device__ __forceinline__ void gemm_phase(PG8_LAS unsigned char* lds, const Gemm g, const Sched& S, const Epi& E) {
;     ...
;         for (int t = 0; t < nt; t += 2) {
;             const bool last = (t == nt - 2);
;             const char* a1 = cA + (size_t)(t + 1) * kstep;
;             const char* a2 = last ? nA : cA + (size_t)(t + 2) * kstep; const char* b2 = last ? nB : cB + (size_t)(t + 2) * kstep;
;             const char* a3 = a2 + kstep; const char* b3 = b2 + kstep;
;             if (last && has_next) S.a_ready(nxt);
;             if constexpr (SP2) {
;             PG8_LDB(B0, 0, 0); PG8_LDB(B1, 0, 1); PG8_SCHED; PG8_LDA(At, 0, 0); PG8_STAGE(PG8_SA(1, 1), a1 + hstepA, voffA);
;             PG8_WAIT_V(8); PG8_WAIT_L(0); PG8_BAR; PG8_MMA(0, 0, At, B0); PG8_MMA(0, 1, At, B1); PG8_BAR; PG8_SCHED;
	v_mfma_f32_16x16x32_bf16 v[46:49], v[162:165], v[194:197], v[46:49]
	v_mfma_f32_16x16x32_bf16 v[42:45], v[186:189], v[194:197], v[42:45]
	v_mfma_f32_16x16x32_bf16 v[30:33], v[162:165], v[202:205], v[30:33]
	v_mfma_f32_16x16x32_bf16 v[26:29], v[186:189], v[202:205], v[26:29]
	v_mfma_f32_16x16x32_bf16 v[14:17], v[162:165], v[210:213], v[14:17]
	v_mfma_f32_16x16x32_bf16 v[10:13], v[186:189], v[210:213], v[10:13]
	v_mfma_f32_16x16x32_bf16 v[6:9], v[162:165], v[222:225], v[6:9]
	v_mfma_f32_16x16x32_bf16 v[2:5], v[186:189], v[222:225], v[2:5]
	v_mfma_f32_16x16x32_bf16 v[46:49], v[166:169], v[198:201], v[46:49]
	v_mfma_f32_16x16x32_bf16 v[42:45], v[190:193], v[198:201], v[42:45]
	v_mfma_f32_16x16x32_bf16 v[30:33], v[166:169], v[206:209], v[30:33]
	v_mfma_f32_16x16x32_bf16 v[26:29], v[190:193], v[206:209], v[26:29]
	v_mfma_f32_16x16x32_bf16 v[14:17], v[166:169], v[218:221], v[14:17]
	v_mfma_f32_16x16x32_bf16 v[10:13], v[190:193], v[218:221], v[10:13]
	v_mfma_f32_16x16x32_bf16 v[6:9], v[166:169], v[226:229], v[6:9]
	v_mfma_f32_16x16x32_bf16 v[2:5], v[190:193], v[226:229], v[2:5]
	s_setprio 0
	s_add_i32 s29, s29, 2
	s_add_u32 s27, s27, 0x100
	s_addc_u32 s28, s28, 0
	s_cmp_gt_u32 s29, 29
	s_mov_b64 s[56:57], s[6:7]
	s_cbranch_scc0 .Lk3_Y
	s_branch .Lk3_exit
.Lk3_Xz:
	ds_read_b128 v[146:149], v175
	ds_read_b128 v[150:153], v175 offset:1024
	ds_read_b128 v[154:157], v175 offset:2048
	ds_read_b128 v[158:161], v175 offset:3072
	ds_read_b128 v[162:165], v176
	ds_read_b128 v[166:169], v176 offset:1024
	ds_read_b128 v[186:189], v176 offset:2048
	ds_read_b128 v[190:193], v176 offset:3072
	s_add_u32 s6, s56, 0x100
	s_addc_u32 s7, s57, 0
	s_cmp_eq_u32 s29, 28
	s_cselect_b32 s61, s53, s7
	s_cselect_b32 s60, s52, s6
	s_cselect_b32 s59, s15, s28
	s_cselect_b32 s58, s26, s27
	ds_read_b128 v[194:197], v177
	ds_read_b128 v[198:201], v177 offset:1024
	ds_read_b128 v[202:205], v177 offset:2048
	ds_read_b128 v[206:209], v177 offset:3072
	ds_read_b128 v[210:213], v177 offset:4096
	ds_read_b128 v[218:221], v177 offset:5120
	ds_read_b128 v[222:225], v177 offset:6144
	ds_read_b128 v[226:229], v177 offset:7168
	s_add_i32 m0, s65, 0xc000
	s_nop 0
	global_load_lds_dwordx4 v138, s[56:57]
	s_add_i32 m0, s65, 0xe000
	s_nop 0
	global_load_lds_dwordx4 v140, s[56:57]
	s_waitcnt vmcnt(8)
	s_waitcnt lgkmcnt(0)
	s_setprio 1
	s_waitcnt lgkmcnt(0)
	v_mfma_f32_16x16x32_bf16 v[126:129], v[146:149], v[194:197], 0
	v_mfma_f32_16x16x32_bf16 v[122:125], v[154:157], v[194:197], 0
	v_mfma_f32_16x16x32_bf16 v[118:121], v[146:149], v[202:205], 0
	v_mfma_f32_16x16x32_bf16 v[114:117], v[154:157], v[202:205], 0
	v_mfma_f32_16x16x32_bf16 v[110:113], v[146:149], v[210:213], 0
	v_mfma_f32_16x16x32_bf16 v[102:105], v[154:157], v[210:213], 0
	v_mfma_f32_16x16x32_bf16 v[94:97], v[146:149], v[222:225], 0
	v_mfma_f32_16x16x32_bf16 v[86:89], v[154:157], v[222:225], 0
	v_mfma_f32_16x16x32_bf16 v[126:129], v[150:153], v[198:201], v[126:129]
	v_mfma_f32_16x16x32_bf16 v[122:125], v[158:161], v[198:201], v[122:125]
	v_mfma_f32_16x16x32_bf16 v[118:121], v[150:153], v[206:209], v[118:121]
	v_mfma_f32_16x16x32_bf16 v[114:117], v[158:161], v[206:209], v[114:117]
	v_mfma_f32_16x16x32_bf16 v[110:113], v[150:153], v[218:221], v[110:113]
	v_mfma_f32_16x16x32_bf16 v[102:105], v[158:161], v[218:221], v[102:105]
	v_mfma_f32_16x16x32_bf16 v[94:97], v[150:153], v[226:229], v[94:97]
	v_mfma_f32_16x16x32_bf16 v[86:89], v[158:161], v[226:229], v[86:89]
	s_setprio 0
	s_setprio 1
	v_mfma_f32_16x16x32_bf16 v[106:109], v[162:165], v[194:197], 0
	v_mfma_f32_16x16x32_bf16 v[98:101], v[186:189], v[194:197], 0
	v_mfma_f32_16x16x32_bf16 v[90:93], v[162:165], v[202:205], 0
	v_mfma_f32_16x16x32_bf16 v[82:85], v[186:189], v[202:205], 0
	v_mfma_f32_16x16x32_bf16 v[78:81], v[162:165], v[210:213], 0
	v_mfma_f32_16x16x32_bf16 v[74:77], v[186:189], v[210:213], 0
	v_mfma_f32_16x16x32_bf16 v[70:73], v[162:165], v[222:225], 0
	v_mfma_f32_16x16x32_bf16 v[66:69], v[186:189], v[222:225], 0
	v_mfma_f32_16x16x32_bf16 v[106:109], v[166:169], v[198:201], v[106:109]
	v_mfma_f32_16x16x32_bf16 v[98:101], v[190:193], v[198:201], v[98:101]
	v_mfma_f32_16x16x32_bf16 v[90:93], v[166:169], v[206:209], v[90:93]
	v_mfma_f32_16x16x32_bf16 v[82:85], v[190:193], v[206:209], v[82:85]
	v_mfma_f32_16x16x32_bf16 v[78:81], v[166:169], v[218:221], v[78:81]
	v_mfma_f32_16x16x32_bf16 v[74:77], v[190:193], v[218:221], v[74:77]
	v_mfma_f32_16x16x32_bf16 v[70:73], v[166:169], v[226:229], v[70:73]
	v_mfma_f32_16x16x32_bf16 v[66:69], v[190:193], v[226:229], v[66:69]
	s_setprio 0
	s_barrier
; #define PG8_STAGE(bufoff, gbase, voff) do { _Pragma("unroll") for (int _i = 0; _i < 2; ++_i) \
;         __builtin_amdgcn_global_load_lds((const unsigned*)((const char*)(gbase) + (voff)[_i]), (PG8_LAS unsigned*)(lds + (bufoff) + ldsw + _i * 8192), 16, 0, 0); } while (0)
; #define PG8_LDA(dst, b, h) do { _Pragma("unroll") for (int m = 0; m < 4; ++m) _Pragma("unroll") for (int k = 0; k < 2; ++k) dst[m][k] = *(const PG8_LAS bf16x8*)(lds + PG8_SA(b, h) + aoff + m * 2048 + k * 1024); } while (0)
; #define PG8_LDB(dst, b, h) do { _Pragma("unroll") for (int n = 0; n < 2; ++n) _Pragma("unroll") for (int k = 0; k < 2; ++k) dst[n][k] = *(const PG8_LAS bf16x8*)(lds + PG8_SB(b, h) + boff + n * 2048 + k * 1024); } while (0)
; #define PG8_WAIT_V(n) asm volatile("s_waitcnt vmcnt(" #n ")" ::: "memory")
; #define PG8_WAIT_L(n) asm volatile("s_waitcnt lgkmcnt(" #n ")" ::: "memory")
; #define PG8_BAR __builtin_amdgcn_s_barrier()
; #define PG8_SCHED __builtin_amdgcn_sched_barrier(0)
; template <class Epi, class Sched, bool ALIGN_EPI = false, bool SP2 = false, bool F8 = false>
; __device__ __forceinline__ void gemm_phase(PG8_LAS unsigned char* lds, const Gemm g, const Sched& S, const Epi& E) {
;     ...
;             PG8_LDA(At, 0, 1); PG8_STAGE(PG8_SB(0, 0), b2, voffB); PG8_STAGE(PG8_SB(0, 1), b2 + hstep, voffB); PG8_STAGE(PG8_SA(0, 0), a2, voffA);
;             PG8_WAIT_V(8); PG8_WAIT_L(0); PG8_BAR; PG8_MMA(1, 0, At, B0); PG8_MMA(1, 1, At, B1); PG8_BAR; PG8_SCHED;
;             PG8_LDB(B0, 1, 0); PG8_LDB(B1, 1, 1); PG8_SCHED; PG8_LDA(At, 1, 0); PG8_STAGE(PG8_SA(0, 1), a2 + hstepA, voffA);
;             PG8_WAIT_V(8); PG8_WAIT_L(0); PG8_BAR; PG8_MMA(0, 0, At, B0); PG8_MMA(0, 1, At, B1); PG8_BAR; PG8_SCHED;
	ds_read_b128 v[194:197], v177 offset:16384
	ds_read_b128 v[198:201], v177 offset:17408
	ds_read_b128 v[202:205], v177 offset:18432
	ds_read_b128 v[206:209], v177 offset:19456
	ds_read_b128 v[210:213], v177 offset:20480
	ds_read_b128 v[218:221], v177 offset:21504
	ds_read_b128 v[222:225], v177 offset:22528
	ds_read_b128 v[226:229], v177 offset:23552
	s_add_u32 s98, s58, 0x80000
	s_addc_u32 s99, s59, 0
	s_add_i32 s100, s75, s62
	s_add_i32 s101, s76, s62
	s_mov_b32 m0, s100
	s_nop 0
	global_load_lds_dwordx4 v134, s[58:59]
	s_add_i32 m0, s100, 0x2000
	s_nop 0
	global_load_lds_dwordx4 v130, s[58:59]
	s_mov_b32 m0, s101
	s_nop 0
	global_load_lds_dwordx4 v134, s[98:99]
	s_add_i32 m0, s101, 0x2000
	s_nop 0
	global_load_lds_dwordx4 v130, s[98:99]
	s_mov_b32 m0, s65
	s_nop 0
	global_load_lds_dwordx4 v136, s[60:61]
	s_mov_b32 m0, s66
	s_nop 0
	global_load_lds_dwordx4 v132, s[60:61]
	s_waitcnt vmcnt(8)
	s_waitcnt lgkmcnt(0)
	s_setprio 1
	s_waitcnt lgkmcnt(0)
	v_mfma_f32_16x16x32_bf16 v[62:65], v[146:149], v[194:197], 0
	v_mfma_f32_16x16x32_bf16 v[58:61], v[154:157], v[194:197], 0
	v_mfma_f32_16x16x32_bf16 v[54:57], v[146:149], v[202:205], 0
	v_mfma_f32_16x16x32_bf16 v[50:53], v[154:157], v[202:205], 0
	v_mfma_f32_16x16x32_bf16 v[38:41], v[146:149], v[210:213], 0
	v_mfma_f32_16x16x32_bf16 v[34:37], v[154:157], v[210:213], 0
	v_mfma_f32_16x16x32_bf16 v[22:25], v[146:149], v[222:225], 0
	v_mfma_f32_16x16x32_bf16 v[18:21], v[154:157], v[222:225], 0
	v_mfma_f32_16x16x32_bf16 v[62:65], v[150:153], v[198:201], v[62:65]
	v_mfma_f32_16x16x32_bf16 v[58:61], v[158:161], v[198:201], v[58:61]
	v_mfma_f32_16x16x32_bf16 v[54:57], v[150:153], v[206:209], v[54:57]
	v_mfma_f32_16x16x32_bf16 v[50:53], v[158:161], v[206:209], v[50:53]
	v_mfma_f32_16x16x32_bf16 v[38:41], v[150:153], v[218:221], v[38:41]
	v_mfma_f32_16x16x32_bf16 v[34:37], v[158:161], v[218:221], v[34:37]
	v_mfma_f32_16x16x32_bf16 v[22:25], v[150:153], v[226:229], v[22:25]
	v_mfma_f32_16x16x32_bf16 v[18:21], v[158:161], v[226:229], v[18:21]
	s_setprio 0
	s_setprio 1
	v_mfma_f32_16x16x32_bf16 v[46:49], v[162:165], v[194:197], 0
	v_mfma_f32_16x16x32_bf16 v[42:45], v[186:189], v[194:197], 0
	v_mfma_f32_16x16x32_bf16 v[30:33], v[162:165], v[202:205], 0
	v_mfma_f32_16x16x32_bf16 v[26:29], v[186:189], v[202:205], 0
	v_mfma_f32_16x16x32_bf16 v[14:17], v[162:165], v[210:213], 0
	v_mfma_f32_16x16x32_bf16 v[10:13], v[186:189], v[210:213], 0
	v_mfma_f32_16x16x32_bf16 v[6:9], v[162:165], v[222:225], 0
	v_mfma_f32_16x16x32_bf16 v[2:5], v[186:189], v[222:225], 0
	v_mfma_f32_16x16x32_bf16 v[46:49], v[166:169], v[198:201], v[46:49]
	v_mfma_f32_16x16x32_bf16 v[42:45], v[190:193], v[198:201], v[42:45]
	v_mfma_f32_16x16x32_bf16 v[30:33], v[166:169], v[206:209], v[30:33]
	v_mfma_f32_16x16x32_bf16 v[26:29], v[190:193], v[206:209], v[26:29]
	v_mfma_f32_16x16x32_bf16 v[14:17], v[166:169], v[218:221], v[14:17]
	v_mfma_f32_16x16x32_bf16 v[10:13], v[190:193], v[218:221], v[10:13]
	v_mfma_f32_16x16x32_bf16 v[6:9], v[166:169], v[226:229], v[6:9]
	v_mfma_f32_16x16x32_bf16 v[2:5], v[190:193], v[226:229], v[2:5]
	s_setprio 0
	s_barrier
	s_add_i32 s33, 0, 0x18000
	s_add_i32 s36, 0, 0x1c000
	v_add_u32_e32 v158, s33, v174
	v_add_u32_e32 v185, s36, v174
	ds_read_b128 v[146:149], v158
	ds_read_b128 v[150:153], v158 offset:1024
	ds_read_b128 v[154:157], v158 offset:2048
	ds_read_b128 v[158:161], v158 offset:3072
	ds_read_b128 v[162:165], v185
	ds_read_b128 v[166:169], v185 offset:1024
	ds_read_b128 v[186:189], v185 offset:2048
	ds_read_b128 v[190:193], v185 offset:3072
	ds_read_b128 v[194:197], v177 offset:32768
	ds_read_b128 v[198:201], v177 offset:33792
	ds_read_b128 v[202:205], v177 offset:34816
	ds_read_b128 v[206:209], v177 offset:35840
	ds_read_b128 v[210:213], v177 offset:36864
	ds_read_b128 v[218:221], v177 offset:37888
	ds_read_b128 v[222:225], v177 offset:38912
	ds_read_b128 v[226:229], v177 offset:39936
	s_add_u32 s98, s60, 0x100000
	s_addc_u32 s99, s61, 0
	s_mov_b32 m0, s67
	s_nop 0
	global_load_lds_dwordx4 v136, s[98:99]
	s_mov_b32 m0, s68
	s_nop 0
	global_load_lds_dwordx4 v132, s[98:99]
	s_waitcnt vmcnt(8)
	s_waitcnt lgkmcnt(0)
	s_setprio 1
	s_waitcnt lgkmcnt(0)
	v_mfma_f32_16x16x32_bf16 v[126:129], v[146:149], v[194:197], v[126:129]
	v_mfma_f32_16x16x32_bf16 v[122:125], v[154:157], v[194:197], v[122:125]
	v_mfma_f32_16x16x32_bf16 v[118:121], v[146:149], v[202:205], v[118:121]
	v_mfma_f32_16x16x32_bf16 v[114:117], v[154:157], v[202:205], v[114:117]
	v_mfma_f32_16x16x32_bf16 v[110:113], v[146:149], v[210:213], v[110:113]
	v_mfma_f32_16x16x32_bf16 v[102:105], v[154:157], v[210:213], v[102:105]
	v_mfma_f32_16x16x32_bf16 v[94:97], v[146:149], v[222:225], v[94:97]
	v_mfma_f32_16x16x32_bf16 v[86:89], v[154:157], v[222:225], v[86:89]
	v_mfma_f32_16x16x32_bf16 v[126:129], v[150:153], v[198:201], v[126:129]
	v_mfma_f32_16x16x32_bf16 v[122:125], v[158:161], v[198:201], v[122:125]
	v_mfma_f32_16x16x32_bf16 v[118:121], v[150:153], v[206:209], v[118:121]
	v_mfma_f32_16x16x32_bf16 v[114:117], v[158:161], v[206:209], v[114:117]
	v_mfma_f32_16x16x32_bf16 v[110:113], v[150:153], v[218:221], v[110:113]
	v_mfma_f32_16x16x32_bf16 v[102:105], v[158:161], v[218:221], v[102:105]
	v_mfma_f32_16x16x32_bf16 v[94:97], v[150:153], v[226:229], v[94:97]
	v_mfma_f32_16x16x32_bf16 v[86:89], v[158:161], v[226:229], v[86:89]
	s_setprio 0
	s_setprio 1
	v_mfma_f32_16x16x32_bf16 v[106:109], v[162:165], v[194:197], v[106:109]
	v_mfma_f32_16x16x32_bf16 v[98:101], v[186:189], v[194:197], v[98:101]
	v_mfma_f32_16x16x32_bf16 v[90:93], v[162:165], v[202:205], v[90:93]
	v_mfma_f32_16x16x32_bf16 v[82:85], v[186:189], v[202:205], v[82:85]
	v_mfma_f32_16x16x32_bf16 v[78:81], v[162:165], v[210:213], v[78:81]
	v_mfma_f32_16x16x32_bf16 v[74:77], v[186:189], v[210:213], v[74:77]
	v_mfma_f32_16x16x32_bf16 v[70:73], v[162:165], v[222:225], v[70:73]
	v_mfma_f32_16x16x32_bf16 v[66:69], v[186:189], v[222:225], v[66:69]
	v_mfma_f32_16x16x32_bf16 v[106:109], v[166:169], v[198:201], v[106:109]
	v_mfma_f32_16x16x32_bf16 v[98:101], v[190:193], v[198:201], v[98:101]
	v_mfma_f32_16x16x32_bf16 v[90:93], v[166:169], v[206:209], v[90:93]
	v_mfma_f32_16x16x32_bf16 v[82:85], v[190:193], v[206:209], v[82:85]
	v_mfma_f32_16x16x32_bf16 v[78:81], v[166:169], v[218:221], v[78:81]
	v_mfma_f32_16x16x32_bf16 v[74:77], v[190:193], v[218:221], v[74:77]
	v_mfma_f32_16x16x32_bf16 v[70:73], v[166:169], v[226:229], v[70:73]
	v_mfma_f32_16x16x32_bf16 v[66:69], v[190:193], v[226:229], v[66:69]
	s_setprio 0
	s_barrier
; #define PG8_STAGE(bufoff, gbase, voff) do { _Pragma("unroll") for (int _i = 0; _i < 2; ++_i) \
;         __builtin_amdgcn_global_load_lds((const unsigned*)((const char*)(gbase) + (voff)[_i]), (PG8_LAS unsigned*)(lds + (bufoff) + ldsw + _i * 8192), 16, 0, 0); } while (0)
; #define PG8_LDA(dst, b, h) do { _Pragma("unroll") for (int m = 0; m < 4; ++m) _Pragma("unroll") for (int k = 0; k < 2; ++k) dst[m][k] = *(const PG8_LAS bf16x8*)(lds + PG8_SA(b, h) + aoff + m * 2048 + k * 1024); } while (0)
; #define PG8_LDB(dst, b, h) do { _Pragma("unroll") for (int n = 0; n < 2; ++n) _Pragma("unroll") for (int k = 0; k < 2; ++k) dst[n][k] = *(const PG8_LAS bf16x8*)(lds + PG8_SB(b, h) + boff + n * 2048 + k * 1024); } while (0)
; #define PG8_WAIT_V(n) asm volatile("s_waitcnt vmcnt(" #n ")" ::: "memory")
; #define PG8_WAIT_L(n) asm volatile("s_waitcnt lgkmcnt(" #n ")" ::: "memory")
; #define PG8_BAR __builtin_amdgcn_s_barrier()
; #define PG8_SCHED __builtin_amdgcn_sched_barrier(0)
; template <class Epi, class Sched, bool ALIGN_EPI = false, bool SP2 = false, bool F8 = false>
; __device__ __forceinline__ void gemm_phase(PG8_LAS unsigned char* lds, const Gemm g, const Sched& S, const Epi& E) {
;     ...
;             PG8_LDB(B0, 0, 0); PG8_LDB(B1, 0, 1); PG8_SCHED; PG8_LDA(At, 0, 0); PG8_STAGE(PG8_SA(1, 1), a1 + hstepA, voffA);
;             PG8_WAIT_V(8); PG8_WAIT_L(0); PG8_BAR; PG8_MMA(0, 0, At, B0); PG8_MMA(0, 1, At, B1); PG8_BAR; PG8_SCHED;
;     ...
;             PG8_LDA(At, 1, 1); PG8_STAGE(PG8_SB(1, 0), b3, voffB); PG8_STAGE(PG8_SB(1, 1), b3 + hstep, voffB); PG8_STAGE(PG8_SA(1, 0), a3, voffA);
;             PG8_WAIT_V(8); PG8_WAIT_L(0); PG8_BAR; PG8_MMA(1, 0, At, B0); PG8_MMA(1, 1, At, B1); PG8_BAR; PG8_SCHED;
	ds_read_b128 v[194:197], v177 offset:49152
	ds_read_b128 v[198:201], v177 offset:50176
	ds_read_b128 v[202:205], v177 offset:51200
	ds_read_b128 v[206:209], v177 offset:52224
	ds_read_b128 v[210:213], v177 offset:53248
	ds_read_b128 v[218:221], v177 offset:54272
	ds_read_b128 v[222:225], v177 offset:55296
	ds_read_b128 v[226:229], v177 offset:56320
	s_add_u32 s98, s58, 0x80
	s_addc_u32 s99, s59, 0
	s_add_u32 s100, s58, 0x80080
	s_addc_u32 s101, s59, 0
	s_add_u32 s24, s60, 0x80
	s_addc_u32 s25, s61, 0
	s_add_i32 m0, s62, 0x18000
	s_nop 0
	global_load_lds_dwordx4 v134, s[98:99]
	s_add_i32 m0, s62, 0x1a000
	s_nop 0
	global_load_lds_dwordx4 v130, s[98:99]
	s_add_i32 m0, s62, 0x1c000
	s_nop 0
	global_load_lds_dwordx4 v134, s[100:101]
	s_add_i32 m0, s62, 0x1e000
	s_nop 0
	global_load_lds_dwordx4 v130, s[100:101]
	s_mov_b32 m0, s71
	s_nop 0
	global_load_lds_dwordx4 v136, s[24:25]
	s_mov_b32 m0, s72
	s_nop 0
	global_load_lds_dwordx4 v132, s[24:25]
	s_waitcnt vmcnt(8)
	s_waitcnt lgkmcnt(0)
	s_setprio 1
	s_waitcnt lgkmcnt(0)
	v_mfma_f32_16x16x32_bf16 v[62:65], v[146:149], v[194:197], v[62:65]
	v_mfma_f32_16x16x32_bf16 v[58:61], v[154:157], v[194:197], v[58:61]
	v_mfma_f32_16x16x32_bf16 v[54:57], v[146:149], v[202:205], v[54:57]
	v_mfma_f32_16x16x32_bf16 v[50:53], v[154:157], v[202:205], v[50:53]
	v_mfma_f32_16x16x32_bf16 v[38:41], v[146:149], v[210:213], v[38:41]
	v_mfma_f32_16x16x32_bf16 v[34:37], v[154:157], v[210:213], v[34:37]
	v_mfma_f32_16x16x32_bf16 v[22:25], v[146:149], v[222:225], v[22:25]
	v_mfma_f32_16x16x32_bf16 v[18:21], v[154:157], v[222:225], v[18:21]
	v_mfma_f32_16x16x32_bf16 v[62:65], v[150:153], v[198:201], v[62:65]
	v_mfma_f32_16x16x32_bf16 v[58:61], v[158:161], v[198:201], v[58:61]
	v_mfma_f32_16x16x32_bf16 v[54:57], v[150:153], v[206:209], v[54:57]
	v_mfma_f32_16x16x32_bf16 v[50:53], v[158:161], v[206:209], v[50:53]
	v_mfma_f32_16x16x32_bf16 v[38:41], v[150:153], v[218:221], v[38:41]
	v_mfma_f32_16x16x32_bf16 v[34:37], v[158:161], v[218:221], v[34:37]
	v_mfma_f32_16x16x32_bf16 v[22:25], v[150:153], v[226:229], v[22:25]
	v_mfma_f32_16x16x32_bf16 v[18:21], v[158:161], v[226:229], v[18:21]
	s_setprio 0
	s_setprio 1
	v_mfma_f32_16x16x32_bf16 v[46:49], v[162:165], v[194:197], v[46:49]
	v_mfma_f32_16x16x32_bf16 v[42:45], v[186:189], v[194:197], v[42:45]
	v_mfma_f32_16x16x32_bf16 v[30:33], v[162:165], v[202:205], v[30:33]
	v_mfma_f32_16x16x32_bf16 v[26:29], v[186:189], v[202:205], v[26:29]
	v_mfma_f32_16x16x32_bf16 v[14:17], v[162:165], v[210:213], v[14:17]
	v_mfma_f32_16x16x32_bf16 v[10:13], v[186:189], v[210:213], v[10:13]
	v_mfma_f32_16x16x32_bf16 v[6:9], v[162:165], v[222:225], v[6:9]
	v_mfma_f32_16x16x32_bf16 v[2:5], v[186:189], v[222:225], v[2:5]
	v_mfma_f32_16x16x32_bf16 v[46:49], v[166:169], v[198:201], v[46:49]
	v_mfma_f32_16x16x32_bf16 v[42:45], v[190:193], v[198:201], v[42:45]
	v_mfma_f32_16x16x32_bf16 v[30:33], v[166:169], v[206:209], v[30:33]
	v_mfma_f32_16x16x32_bf16 v[26:29], v[190:193], v[206:209], v[26:29]
	v_mfma_f32_16x16x32_bf16 v[14:17], v[166:169], v[218:221], v[14:17]
	v_mfma_f32_16x16x32_bf16 v[10:13], v[190:193], v[218:221], v[10:13]
	v_mfma_f32_16x16x32_bf16 v[6:9], v[166:169], v[226:229], v[6:9]
	v_mfma_f32_16x16x32_bf16 v[2:5], v[190:193], v[226:229], v[2:5]
	s_setprio 0
	s_barrier
	s_add_i32 s29, s29, 2
	s_add_u32 s27, s27, 0x100
	s_addc_u32 s28, s28, 0
	s_cmp_gt_u32 s29, 29
	s_mov_b64 s[56:57], s[6:7]
	s_branch .LBB0_917
.Lk3_Yz:
	ds_read_b128 v[146:149], v175
	ds_read_b128 v[150:153], v175 offset:1024
	ds_read_b128 v[154:157], v175 offset:2048
	ds_read_b128 v[158:161], v175 offset:3072
	ds_read_b128 v[162:165], v176
	ds_read_b128 v[166:169], v176 offset:1024
	ds_read_b128 v[186:189], v176 offset:2048
	ds_read_b128 v[190:193], v176 offset:3072
	s_add_u32 s6, s56, 0x100
	s_addc_u32 s7, s57, 0
	s_cmp_eq_u32 s29, 28
	s_cselect_b32 s61, s53, s7
	s_cselect_b32 s60, s52, s6
	s_cselect_b32 s59, s15, s28
	s_cselect_b32 s58, s26, s27
	ds_read_b128 v[194:197], v177
	ds_read_b128 v[198:201], v177 offset:1024
	ds_read_b128 v[202:205], v177 offset:2048
	ds_read_b128 v[206:209], v177 offset:3072
	ds_read_b128 v[210:213], v177 offset:4096
	ds_read_b128 v[218:221], v177 offset:5120
	ds_read_b128 v[222:225], v177 offset:6144
	ds_read_b128 v[226:229], v177 offset:7168
	s_add_i32 m0, s65, 0xc000
	s_nop 0
	global_load_lds_dwordx4 v138, s[56:57]
	s_add_i32 m0, s65, 0xe000
	s_nop 0
	global_load_lds_dwordx4 v140, s[56:57]
	s_waitcnt vmcnt(8)
	s_waitcnt lgkmcnt(0)
	s_barrier
	s_setprio 3
	s_waitcnt lgkmcnt(0)
	v_mfma_f32_16x16x32_bf16 v[126:129], v[146:149], v[194:197], 0
	v_mfma_f32_16x16x32_bf16 v[122:125], v[154:157], v[194:197], 0
	v_mfma_f32_16x16x32_bf16 v[118:121], v[146:149], v[202:205], 0
	v_mfma_f32_16x16x32_bf16 v[114:117], v[154:157], v[202:205], 0
	v_mfma_f32_16x16x32_bf16 v[110:113], v[146:149], v[210:213], 0
	v_mfma_f32_16x16x32_bf16 v[102:105], v[154:157], v[210:213], 0
	v_mfma_f32_16x16x32_bf16 v[94:97], v[146:149], v[222:225], 0
	v_mfma_f32_16x16x32_bf16 v[86:89], v[154:157], v[222:225], 0
	v_mfma_f32_16x16x32_bf16 v[126:129], v[150:153], v[198:201], v[126:129]
	v_mfma_f32_16x16x32_bf16 v[122:125], v[158:161], v[198:201], v[122:125]
	v_mfma_f32_16x16x32_bf16 v[118:121], v[150:153], v[206:209], v[118:121]
	v_mfma_f32_16x16x32_bf16 v[114:117], v[158:161], v[206:209], v[114:117]
	v_mfma_f32_16x16x32_bf16 v[110:113], v[150:153], v[218:221], v[110:113]
	v_mfma_f32_16x16x32_bf16 v[102:105], v[158:161], v[218:221], v[102:105]
	v_mfma_f32_16x16x32_bf16 v[94:97], v[150:153], v[226:229], v[94:97]
	v_mfma_f32_16x16x32_bf16 v[86:89], v[158:161], v[226:229], v[86:89]


; #define PG8_STAGE(bufoff, gbase, voff) do { _Pragma("unroll") for (int _i = 0; _i < 2; ++_i) \
;         __builtin_amdgcn_global_load_lds((const unsigned*)((const char*)(gbase) + (voff)[_i]), (PG8_LAS unsigned*)(lds + (bufoff) + ldsw + _i * 8192), 16, 0, 0); } while (0)
; #define PG8_LDA(dst, b, h) do { _Pragma("unroll") for (int m = 0; m < 4; ++m) _Pragma("unroll") for (int k = 0; k < 2; ++k) dst[m][k] = *(const PG8_LAS bf16x8*)(lds + PG8_SA(b, h) + aoff + m * 2048 + k * 1024); } while (0)
; #define PG8_WAIT_V(n) asm volatile("s_waitcnt vmcnt(" #n ")" ::: "memory")
; #define PG8_WAIT_L(n) asm volatile("s_waitcnt lgkmcnt(" #n ")" ::: "memory")
; #define PG8_BAR __builtin_amdgcn_s_barrier()
; #define PG8_SCHED __builtin_amdgcn_sched_barrier(0)
; template <class Epi, class Sched, bool ALIGN_EPI = false, bool SP2 = false, bool F8 = false>
; __device__ __forceinline__ void gemm_phase(PG8_LAS unsigned char* lds, const Gemm g, const Sched& S, const Epi& E) {
;     ...
;             PG8_WAIT_V(8); PG8_WAIT_L(0); PG8_BAR; PG8_MMA(0, 0, At, B0); PG8_MMA(0, 1, At, B1); PG8_BAR; PG8_SCHED;
;             PG8_LDA(At, 0, 1); PG8_STAGE(PG8_SB(0, 0), b2, voffB); PG8_STAGE(PG8_SB(0, 1), b2 + hstep, voffB); PG8_STAGE(PG8_SA(0, 0), a2, voffA);
;             PG8_WAIT_V(8); PG8_WAIT_L(0); PG8_BAR; PG8_MMA(1, 0, At, B0); PG8_MMA(1, 1, At, B1); PG8_BAR; PG8_SCHED;
	v_mfma_f32_16x16x32_bf16 v[106:109], v[162:165], v[194:197], 0
	v_mfma_f32_16x16x32_bf16 v[98:101], v[186:189], v[194:197], 0
	v_mfma_f32_16x16x32_bf16 v[90:93], v[162:165], v[202:205], 0
	v_mfma_f32_16x16x32_bf16 v[82:85], v[186:189], v[202:205], 0
	v_mfma_f32_16x16x32_bf16 v[78:81], v[162:165], v[210:213], 0
	v_mfma_f32_16x16x32_bf16 v[74:77], v[186:189], v[210:213], 0
	v_mfma_f32_16x16x32_bf16 v[70:73], v[162:165], v[222:225], 0
	v_mfma_f32_16x16x32_bf16 v[66:69], v[186:189], v[222:225], 0
	v_mfma_f32_16x16x32_bf16 v[106:109], v[166:169], v[198:201], v[106:109]
	v_mfma_f32_16x16x32_bf16 v[98:101], v[190:193], v[198:201], v[98:101]
	v_mfma_f32_16x16x32_bf16 v[90:93], v[166:169], v[206:209], v[90:93]
	v_mfma_f32_16x16x32_bf16 v[82:85], v[190:193], v[206:209], v[82:85]
	v_mfma_f32_16x16x32_bf16 v[78:81], v[166:169], v[218:221], v[78:81]
	v_mfma_f32_16x16x32_bf16 v[74:77], v[190:193], v[218:221], v[74:77]
	v_mfma_f32_16x16x32_bf16 v[70:73], v[166:169], v[226:229], v[70:73]
	v_mfma_f32_16x16x32_bf16 v[66:69], v[190:193], v[226:229], v[66:69]
	s_setprio 0
	ds_read_b128 v[194:197], v177 offset:16384
	ds_read_b128 v[198:201], v177 offset:17408
	ds_read_b128 v[202:205], v177 offset:18432
	ds_read_b128 v[206:209], v177 offset:19456
	ds_read_b128 v[210:213], v177 offset:20480
	ds_read_b128 v[218:221], v177 offset:21504
	ds_read_b128 v[222:225], v177 offset:22528
	ds_read_b128 v[226:229], v177 offset:23552
	s_add_u32 s98, s58, 0x80000
	s_addc_u32 s99, s59, 0
	s_add_i32 s100, s75, s62
	s_add_i32 s101, s76, s62
	s_mov_b32 m0, s100
	s_nop 0
	global_load_lds_dwordx4 v134, s[58:59]
	s_add_i32 m0, s100, 0x2000
	s_nop 0
	global_load_lds_dwordx4 v130, s[58:59]
	s_mov_b32 m0, s101
	s_nop 0
	global_load_lds_dwordx4 v134, s[98:99]
	s_add_i32 m0, s101, 0x2000
	s_nop 0
	global_load_lds_dwordx4 v130, s[98:99]
	s_mov_b32 m0, s65
	s_nop 0
	global_load_lds_dwordx4 v136, s[60:61]
	s_mov_b32 m0, s66
	s_nop 0
	global_load_lds_dwordx4 v132, s[60:61]
	s_waitcnt vmcnt(8)
	s_waitcnt lgkmcnt(0)
	s_barrier
	s_setprio 3
	s_waitcnt lgkmcnt(0)
	v_mfma_f32_16x16x32_bf16 v[62:65], v[146:149], v[194:197], 0
	v_mfma_f32_16x16x32_bf16 v[58:61], v[154:157], v[194:197], 0
	v_mfma_f32_16x16x32_bf16 v[54:57], v[146:149], v[202:205], 0
	v_mfma_f32_16x16x32_bf16 v[50:53], v[154:157], v[202:205], 0
	v_mfma_f32_16x16x32_bf16 v[38:41], v[146:149], v[210:213], 0
	v_mfma_f32_16x16x32_bf16 v[34:37], v[154:157], v[210:213], 0
	v_mfma_f32_16x16x32_bf16 v[22:25], v[146:149], v[222:225], 0
	v_mfma_f32_16x16x32_bf16 v[18:21], v[154:157], v[222:225], 0
	v_mfma_f32_16x16x32_bf16 v[62:65], v[150:153], v[198:201], v[62:65]
	v_mfma_f32_16x16x32_bf16 v[58:61], v[158:161], v[198:201], v[58:61]
	v_mfma_f32_16x16x32_bf16 v[54:57], v[150:153], v[206:209], v[54:57]
	v_mfma_f32_16x16x32_bf16 v[50:53], v[158:161], v[206:209], v[50:53]
	v_mfma_f32_16x16x32_bf16 v[38:41], v[150:153], v[218:221], v[38:41]
	v_mfma_f32_16x16x32_bf16 v[34:37], v[158:161], v[218:221], v[34:37]
	v_mfma_f32_16x16x32_bf16 v[22:25], v[150:153], v[226:229], v[22:25]
	v_mfma_f32_16x16x32_bf16 v[18:21], v[158:161], v[226:229], v[18:21]


; #define PG8_STAGE(bufoff, gbase, voff) do { _Pragma("unroll") for (int _i = 0; _i < 2; ++_i) \
;         __builtin_amdgcn_global_load_lds((const unsigned*)((const char*)(gbase) + (voff)[_i]), (PG8_LAS unsigned*)(lds + (bufoff) + ldsw + _i * 8192), 16, 0, 0); } while (0)
; #define PG8_LDA(dst, b, h) do { _Pragma("unroll") for (int m = 0; m < 4; ++m) _Pragma("unroll") for (int k = 0; k < 2; ++k) dst[m][k] = *(const PG8_LAS bf16x8*)(lds + PG8_SA(b, h) + aoff + m * 2048 + k * 1024); } while (0)
; #define PG8_LDB(dst, b, h) do { _Pragma("unroll") for (int n = 0; n < 2; ++n) _Pragma("unroll") for (int k = 0; k < 2; ++k) dst[n][k] = *(const PG8_LAS bf16x8*)(lds + PG8_SB(b, h) + boff + n * 2048 + k * 1024); } while (0)
; #define PG8_WAIT_V(n) asm volatile("s_waitcnt vmcnt(" #n ")" ::: "memory")
; #define PG8_WAIT_L(n) asm volatile("s_waitcnt lgkmcnt(" #n ")" ::: "memory")
; #define PG8_BAR __builtin_amdgcn_s_barrier()
; #define PG8_SCHED __builtin_amdgcn_sched_barrier(0)
; template <class Epi, class Sched, bool ALIGN_EPI = false, bool SP2 = false, bool F8 = false>
; __device__ __forceinline__ void gemm_phase(PG8_LAS unsigned char* lds, const Gemm g, const Sched& S, const Epi& E) {
;     ...
;             PG8_WAIT_V(8); PG8_WAIT_L(0); PG8_BAR; PG8_MMA(1, 0, At, B0); PG8_MMA(1, 1, At, B1); PG8_BAR; PG8_SCHED;
;             PG8_LDB(B0, 1, 0); PG8_LDB(B1, 1, 1); PG8_SCHED; PG8_LDA(At, 1, 0); PG8_STAGE(PG8_SA(0, 1), a2 + hstepA, voffA);
;             PG8_WAIT_V(8); PG8_WAIT_L(0); PG8_BAR; PG8_MMA(0, 0, At, B0); PG8_MMA(0, 1, At, B1); PG8_BAR; PG8_SCHED;
	v_mfma_f32_16x16x32_bf16 v[46:49], v[162:165], v[194:197], 0
	v_mfma_f32_16x16x32_bf16 v[42:45], v[186:189], v[194:197], 0
	v_mfma_f32_16x16x32_bf16 v[30:33], v[162:165], v[202:205], 0
	v_mfma_f32_16x16x32_bf16 v[26:29], v[186:189], v[202:205], 0
	v_mfma_f32_16x16x32_bf16 v[14:17], v[162:165], v[210:213], 0
	v_mfma_f32_16x16x32_bf16 v[10:13], v[186:189], v[210:213], 0
	v_mfma_f32_16x16x32_bf16 v[6:9], v[162:165], v[222:225], 0
	v_mfma_f32_16x16x32_bf16 v[2:5], v[186:189], v[222:225], 0
	v_mfma_f32_16x16x32_bf16 v[46:49], v[166:169], v[198:201], v[46:49]
	v_mfma_f32_16x16x32_bf16 v[42:45], v[190:193], v[198:201], v[42:45]
	v_mfma_f32_16x16x32_bf16 v[30:33], v[166:169], v[206:209], v[30:33]
	v_mfma_f32_16x16x32_bf16 v[26:29], v[190:193], v[206:209], v[26:29]
	v_mfma_f32_16x16x32_bf16 v[14:17], v[166:169], v[218:221], v[14:17]
	v_mfma_f32_16x16x32_bf16 v[10:13], v[190:193], v[218:221], v[10:13]
	v_mfma_f32_16x16x32_bf16 v[6:9], v[166:169], v[226:229], v[6:9]
	v_mfma_f32_16x16x32_bf16 v[2:5], v[190:193], v[226:229], v[2:5]
	s_setprio 0
	s_add_i32 s33, 0, 0x18000
	s_add_i32 s36, 0, 0x1c000
	v_add_u32_e32 v158, s33, v174
	v_add_u32_e32 v185, s36, v174
	ds_read_b128 v[146:149], v158
	ds_read_b128 v[150:153], v158 offset:1024
	ds_read_b128 v[154:157], v158 offset:2048
	ds_read_b128 v[158:161], v158 offset:3072
	ds_read_b128 v[162:165], v185
	ds_read_b128 v[166:169], v185 offset:1024
	ds_read_b128 v[186:189], v185 offset:2048
	ds_read_b128 v[190:193], v185 offset:3072
	ds_read_b128 v[194:197], v177 offset:32768
	ds_read_b128 v[198:201], v177 offset:33792
	ds_read_b128 v[202:205], v177 offset:34816
	ds_read_b128 v[206:209], v177 offset:35840
	ds_read_b128 v[210:213], v177 offset:36864
	ds_read_b128 v[218:221], v177 offset:37888
	ds_read_b128 v[222:225], v177 offset:38912
	ds_read_b128 v[226:229], v177 offset:39936
	s_add_u32 s98, s60, 0x100000
	s_addc_u32 s99, s61, 0
	s_mov_b32 m0, s67
	s_nop 0
	global_load_lds_dwordx4 v136, s[98:99]
	s_mov_b32 m0, s68
	s_nop 0
	global_load_lds_dwordx4 v132, s[98:99]
	s_waitcnt vmcnt(8)
	s_waitcnt lgkmcnt(0)
	s_barrier
	s_setprio 3
	s_waitcnt lgkmcnt(0)
	v_mfma_f32_16x16x32_bf16 v[126:129], v[146:149], v[194:197], v[126:129]
	v_mfma_f32_16x16x32_bf16 v[122:125], v[154:157], v[194:197], v[122:125]
	v_mfma_f32_16x16x32_bf16 v[118:121], v[146:149], v[202:205], v[118:121]
	v_mfma_f32_16x16x32_bf16 v[114:117], v[154:157], v[202:205], v[114:117]
	v_mfma_f32_16x16x32_bf16 v[110:113], v[146:149], v[210:213], v[110:113]
	v_mfma_f32_16x16x32_bf16 v[102:105], v[154:157], v[210:213], v[102:105]
	v_mfma_f32_16x16x32_bf16 v[94:97], v[146:149], v[222:225], v[94:97]
	v_mfma_f32_16x16x32_bf16 v[86:89], v[154:157], v[222:225], v[86:89]
	v_mfma_f32_16x16x32_bf16 v[126:129], v[150:153], v[198:201], v[126:129]
	v_mfma_f32_16x16x32_bf16 v[122:125], v[158:161], v[198:201], v[122:125]
	v_mfma_f32_16x16x32_bf16 v[118:121], v[150:153], v[206:209], v[118:121]
	v_mfma_f32_16x16x32_bf16 v[114:117], v[158:161], v[206:209], v[114:117]
	v_mfma_f32_16x16x32_bf16 v[110:113], v[150:153], v[218:221], v[110:113]
	v_mfma_f32_16x16x32_bf16 v[102:105], v[158:161], v[218:221], v[102:105]
	v_mfma_f32_16x16x32_bf16 v[94:97], v[150:153], v[226:229], v[94:97]
	v_mfma_f32_16x16x32_bf16 v[86:89], v[158:161], v[226:229], v[86:89]


; #define PG8_STAGE(bufoff, gbase, voff) do { _Pragma("unroll") for (int _i = 0; _i < 2; ++_i) \
;         __builtin_amdgcn_global_load_lds((const unsigned*)((const char*)(gbase) + (voff)[_i]), (PG8_LAS unsigned*)(lds + (bufoff) + ldsw + _i * 8192), 16, 0, 0); } while (0)
; #define PG8_LDA(dst, b, h) do { _Pragma("unroll") for (int m = 0; m < 4; ++m) _Pragma("unroll") for (int k = 0; k < 2; ++k) dst[m][k] = *(const PG8_LAS bf16x8*)(lds + PG8_SA(b, h) + aoff + m * 2048 + k * 1024); } while (0)
; #define PG8_WAIT_V(n) asm volatile("s_waitcnt vmcnt(" #n ")" ::: "memory")
; #define PG8_WAIT_L(n) asm volatile("s_waitcnt lgkmcnt(" #n ")" ::: "memory")
; #define PG8_BAR __builtin_amdgcn_s_barrier()
; #define PG8_SCHED __builtin_amdgcn_sched_barrier(0)
; template <class Epi, class Sched, bool ALIGN_EPI = false, bool SP2 = false, bool F8 = false>
; __device__ __forceinline__ void gemm_phase(PG8_LAS unsigned char* lds, const Gemm g, const Sched& S, const Epi& E) {
;     ...
;             PG8_WAIT_V(8); PG8_WAIT_L(0); PG8_BAR; PG8_MMA(0, 0, At, B0); PG8_MMA(0, 1, At, B1); PG8_BAR; PG8_SCHED;
;             PG8_LDA(At, 1, 1); PG8_STAGE(PG8_SB(1, 0), b3, voffB); PG8_STAGE(PG8_SB(1, 1), b3 + hstep, voffB); PG8_STAGE(PG8_SA(1, 0), a3, voffA);
;             PG8_WAIT_V(8); PG8_WAIT_L(0); PG8_BAR; PG8_MMA(1, 0, At, B0); PG8_MMA(1, 1, At, B1); PG8_BAR; PG8_SCHED;
	v_mfma_f32_16x16x32_bf16 v[106:109], v[162:165], v[194:197], v[106:109]
	v_mfma_f32_16x16x32_bf16 v[98:101], v[186:189], v[194:197], v[98:101]
	v_mfma_f32_16x16x32_bf16 v[90:93], v[162:165], v[202:205], v[90:93]
	v_mfma_f32_16x16x32_bf16 v[82:85], v[186:189], v[202:205], v[82:85]
	v_mfma_f32_16x16x32_bf16 v[78:81], v[162:165], v[210:213], v[78:81]
	v_mfma_f32_16x16x32_bf16 v[74:77], v[186:189], v[210:213], v[74:77]
	v_mfma_f32_16x16x32_bf16 v[70:73], v[162:165], v[222:225], v[70:73]
	v_mfma_f32_16x16x32_bf16 v[66:69], v[186:189], v[222:225], v[66:69]
	v_mfma_f32_16x16x32_bf16 v[106:109], v[166:169], v[198:201], v[106:109]
	v_mfma_f32_16x16x32_bf16 v[98:101], v[190:193], v[198:201], v[98:101]
	v_mfma_f32_16x16x32_bf16 v[90:93], v[166:169], v[206:209], v[90:93]
	v_mfma_f32_16x16x32_bf16 v[82:85], v[190:193], v[206:209], v[82:85]
	v_mfma_f32_16x16x32_bf16 v[78:81], v[166:169], v[218:221], v[78:81]
	v_mfma_f32_16x16x32_bf16 v[74:77], v[190:193], v[218:221], v[74:77]
	v_mfma_f32_16x16x32_bf16 v[70:73], v[166:169], v[226:229], v[70:73]
	v_mfma_f32_16x16x32_bf16 v[66:69], v[190:193], v[226:229], v[66:69]
	s_setprio 0
	ds_read_b128 v[194:197], v177 offset:49152
	ds_read_b128 v[198:201], v177 offset:50176
	ds_read_b128 v[202:205], v177 offset:51200
	ds_read_b128 v[206:209], v177 offset:52224
	ds_read_b128 v[210:213], v177 offset:53248
	ds_read_b128 v[218:221], v177 offset:54272
	ds_read_b128 v[222:225], v177 offset:55296
	ds_read_b128 v[226:229], v177 offset:56320
	s_add_u32 s98, s58, 0x80
	s_addc_u32 s99, s59, 0
	s_add_u32 s100, s58, 0x80080
	s_addc_u32 s101, s59, 0
	s_add_u32 s24, s60, 0x80
	s_addc_u32 s25, s61, 0
	s_add_i32 m0, s62, 0x18000
	s_nop 0
	global_load_lds_dwordx4 v134, s[98:99]
	s_add_i32 m0, s62, 0x1a000
	s_nop 0
	global_load_lds_dwordx4 v130, s[98:99]
	s_add_i32 m0, s62, 0x1c000
	s_nop 0
	global_load_lds_dwordx4 v134, s[100:101]
	s_add_i32 m0, s62, 0x1e000
	s_nop 0
	global_load_lds_dwordx4 v130, s[100:101]
	s_mov_b32 m0, s71
	s_nop 0
	global_load_lds_dwordx4 v136, s[24:25]
	s_mov_b32 m0, s72
	s_nop 0
	global_load_lds_dwordx4 v132, s[24:25]
	s_waitcnt vmcnt(8)
	s_waitcnt lgkmcnt(0)
	s_barrier
	s_setprio 3
	s_waitcnt lgkmcnt(0)
	v_mfma_f32_16x16x32_bf16 v[62:65], v[146:149], v[194:197], v[62:65]
	v_mfma_f32_16x16x32_bf16 v[58:61], v[154:157], v[194:197], v[58:61]
	v_mfma_f32_16x16x32_bf16 v[54:57], v[146:149], v[202:205], v[54:57]
	v_mfma_f32_16x16x32_bf16 v[50:53], v[154:157], v[202:205], v[50:53]
	v_mfma_f32_16x16x32_bf16 v[38:41], v[146:149], v[210:213], v[38:41]
	v_mfma_f32_16x16x32_bf16 v[34:37], v[154:157], v[210:213], v[34:37]
	v_mfma_f32_16x16x32_bf16 v[22:25], v[146:149], v[222:225], v[22:25]
	v_mfma_f32_16x16x32_bf16 v[18:21], v[154:157], v[222:225], v[18:21]
	v_mfma_f32_16x16x32_bf16 v[62:65], v[150:153], v[198:201], v[62:65]
	v_mfma_f32_16x16x32_bf16 v[58:61], v[158:161], v[198:201], v[58:61]
	v_mfma_f32_16x16x32_bf16 v[54:57], v[150:153], v[206:209], v[54:57]
	v_mfma_f32_16x16x32_bf16 v[50:53], v[158:161], v[206:209], v[50:53]
	v_mfma_f32_16x16x32_bf16 v[38:41], v[150:153], v[218:221], v[38:41]
	v_mfma_f32_16x16x32_bf16 v[34:37], v[158:161], v[218:221], v[34:37]
	v_mfma_f32_16x16x32_bf16 v[22:25], v[150:153], v[226:229], v[22:25]
	v_mfma_f32_16x16x32_bf16 v[18:21], v[158:161], v[226:229], v[18:21]


; #define PG8_WAIT_V(n) asm volatile("s_waitcnt vmcnt(" #n ")" ::: "memory")
; #define PG8_WAIT_L(n) asm volatile("s_waitcnt lgkmcnt(" #n ")" ::: "memory")
; #define PG8_BAR __builtin_amdgcn_s_barrier()
; #define PG8_SCHED __builtin_amdgcn_sched_barrier(0)
; template <class Epi, class Sched, bool ALIGN_EPI = false, bool SP2 = false, bool F8 = false>
; __device__ __forceinline__ void gemm_phase(PG8_LAS unsigned char* lds, const Gemm g, const Sched& S, const Epi& E) {
;     ...
;         for (int t = 0; t < nt; t += 2) {
;     ...
;             PG8_WAIT_V(8); PG8_WAIT_L(0); PG8_BAR; PG8_MMA(1, 0, At, B0); PG8_MMA(1, 1, At, B1); PG8_BAR; PG8_SCHED;
	v_mfma_f32_16x16x32_bf16 v[46:49], v[162:165], v[194:197], v[46:49]
	v_mfma_f32_16x16x32_bf16 v[42:45], v[186:189], v[194:197], v[42:45]
	v_mfma_f32_16x16x32_bf16 v[30:33], v[162:165], v[202:205], v[30:33]
	v_mfma_f32_16x16x32_bf16 v[26:29], v[186:189], v[202:205], v[26:29]
	v_mfma_f32_16x16x32_bf16 v[14:17], v[162:165], v[210:213], v[14:17]
	v_mfma_f32_16x16x32_bf16 v[10:13], v[186:189], v[210:213], v[10:13]
	v_mfma_f32_16x16x32_bf16 v[6:9], v[162:165], v[222:225], v[6:9]
	v_mfma_f32_16x16x32_bf16 v[2:5], v[186:189], v[222:225], v[2:5]
	v_mfma_f32_16x16x32_bf16 v[46:49], v[166:169], v[198:201], v[46:49]
	v_mfma_f32_16x16x32_bf16 v[42:45], v[190:193], v[198:201], v[42:45]
	v_mfma_f32_16x16x32_bf16 v[30:33], v[166:169], v[206:209], v[30:33]
	v_mfma_f32_16x16x32_bf16 v[26:29], v[190:193], v[206:209], v[26:29]
	v_mfma_f32_16x16x32_bf16 v[14:17], v[166:169], v[218:221], v[14:17]
	v_mfma_f32_16x16x32_bf16 v[10:13], v[190:193], v[218:221], v[10:13]
	v_mfma_f32_16x16x32_bf16 v[6:9], v[166:169], v[226:229], v[6:9]
	v_mfma_f32_16x16x32_bf16 v[2:5], v[190:193], v[226:229], v[2:5]
	s_setprio 0
	s_add_i32 s29, s29, 2
	s_add_u32 s27, s27, 0x100
	s_addc_u32 s28, s28, 0
	s_cmp_gt_u32 s29, 29
	s_mov_b64 s[56:57], s[6:7]
	s_branch .Lk3_Y
